# remove NaN-canonicalising v_max x,x,x from the NSA softmax max-reduction chains (hazard-checked), on top of top-k v2 + paired RMWs
# speedup vs baseline: 1.0104x; 1.0047x over previous
; template <int MODE>
; __device__ __forceinline__ void nsa_soft(f32x4 (&st)[4], const float (&Bl)[16], float cl, bool fast, int keybase, int t, bool sel, float& m2, float& l, f32x4 (&o)[4], float lfin, LAS float* imp, int lane) {
;     ...
;         for (int r = 0; r < 4; ++r) st[tau][r] = __builtin_fmaf(st[tau][r], LOG2E, Bl[tau * 4 + r]);
;     if (!fast) {
; #pragma unroll
;         for (int tau = 0; tau < 4; ++tau)
; #pragma unroll
;             for (int r = 0; r < 4; ++r) { const int off = keybase + 32 * (tau >> 1) + 8 * kg + 4 * (tau & 1) + r;
;                 int dist; bool valid;
;                 if (MODE <= 1) { dist = t - (16 * off + 31); valid = dist >= 0; }
;                 else if (MODE == 2) { dist = t - off; valid = sel && dist >= 0; }
;                 else { dist = t - off; valid = dist >= 0 && dist < 512; }
;                 st[tau][r] = valid ? st[tau][r] : -INFINITY; }
;     }
;     if (MODE == 1) {
;         const float sh = cl - lfin;
; #pragma unroll
;         for (int tau = 0; tau < 4; ++tau) {
; #pragma unroll
;             for (int r = 0; r < 4; ++r) st[tau][r] = __builtin_amdgcn_exp2f(st[tau][r] + sh);
;             float ps = (st[tau][0] + st[tau][1]) + (st[tau][2] + st[tau][3]), p3 = st[tau][3];
;             ps += dppf<DPP_XOR1>(ps); ps += dppf<DPP_XOR2>(ps); p3 += dppf<DPP_XOR1>(p3); p3 += dppf<DPP_XOR2>(p3);
;             const int j0 = (keybase >> 2) + 8 * (tau >> 1) + 2 * kg + (tau & 1);
;             if ((lane & 3) == 0) { const int tk = (lane & 15) >> 2; imp[tk * 256 + j0] += ps; if (j0 + 1 < 256) imp[tk * 256 + j0 + 1] += p3; }
;         }
;     } else {
;         float mloc = fmaxf(fmaxf(fmaxf(st[0][0], st[0][1]), fmaxf(st[0][2], st[0][3])), fmaxf(fmaxf(st[1][0], st[1][1]), fmaxf(st[1][2], st[1][3])));
;         mloc = fmaxf(mloc, fmaxf(fmaxf(fmaxf(st[2][0], st[2][1]), fmaxf(st[2][2], st[2][3])), fmaxf(fmaxf(st[3][0], st[3][1]), fmaxf(st[3][2], st[3][3]))));
;         mloc = xrow16_max(mloc);
;         const float mnew = fmaxf(m2, mloc + cl); const float alpha = __builtin_amdgcn_exp2f(m2 - mnew); m2 = mnew;
;         const float sh = cl - mnew;
;         float ps = 0.f;
; #pragma unroll
;         for (int tau = 0; tau < 4; ++tau)
; #pragma unroll
;             for (int r = 0; r < 4; ++r) { const float p = __builtin_amdgcn_exp2f(st[tau][r] + sh); st[tau][r] = p; ps += p; }
;         l = l * alpha + ps;
.LBB0_909:
	v_max_f32_e32 v53, v66, v67
	v_max_f32_e32 v70, v62, v63
	v_max_f32_e32 v71, v60, v61
	v_max_f32_e32 v72, v58, v59
	v_max_f32_e32 v73, v54, v55
	v_max3_f32 v73, v56, v57, v73
	v_max3_f32 v53, v68, v69, v53
	v_max3_f32 v70, v64, v65, v70
	v_max3_f32 v71, v71, v72, v73
	v_max3_f32 v53, v53, v70, v71
	v_mov_b32_e32 v70, v53
	s_nop 1
	v_permlane16_swap_b32_e32 v53, v70
	v_max_f32_e32 v53, v53, v70
	v_mov_b32_e32 v89, v53
	s_nop 1
	v_permlane32_swap_b32_e32 v53, v89
	v_pk_fma_f32 v[76:77], v[28:29], s[22:23], v[80:81] op_sel_hi:[1,0,1]
	v_pk_fma_f32 v[74:75], v[30:31], s[22:23], v[82:83] op_sel_hi:[1,0,1]
	v_pk_fma_f32 v[72:73], v[32:33], s[22:23], v[84:85] op_sel_hi:[1,0,1]
	v_pk_fma_f32 v[70:71], v[34:35], s[22:23], v[86:87] op_sel_hi:[1,0,1]
	v_pk_fma_f32 v[34:35], v[36:37], s[22:23], v[166:167] op_sel_hi:[1,0,1]
	v_pk_fma_f32 v[32:33], v[38:39], s[22:23], v[168:169] op_sel_hi:[1,0,1]
	v_pk_fma_f32 v[30:31], v[40:41], s[22:23], v[170:171] op_sel_hi:[1,0,1]
	s_andn2_b64 vcc, exec, s[40:41]
	v_pk_fma_f32 v[28:29], v[42:43], s[22:23], v[172:173] op_sel_hi:[1,0,1]
	s_cbranch_vccnz .LBB0_911
	v_cmp_ge_i32_e32 vcc, v24, v180
	s_nop 1
	v_cndmask_b32_e32 v76, v225, v76, vcc
	v_cmp_ge_i32_e32 vcc, v25, v177
	s_nop 1
	v_cndmask_b32_e32 v77, v225, v77, vcc
	v_cmp_ge_i32_e32 vcc, v26, v179
	s_nop 1
	v_cndmask_b32_e32 v74, v225, v74, vcc
	v_cmp_ge_i32_e32 vcc, v27, v176
	s_nop 1
	v_cndmask_b32_e32 v75, v225, v75, vcc
	v_cmp_ge_i32_e32 vcc, v164, v178
	s_nop 1
	v_cndmask_b32_e32 v72, v225, v72, vcc
	v_cmp_ge_i32_e32 vcc, v49, v163
	s_nop 1
	v_cndmask_b32_e32 v73, v225, v73, vcc
	v_cmp_ge_i32_e32 vcc, v164, v174
	s_nop 1
	v_cndmask_b32_e32 v70, v225, v70, vcc
	v_cmp_ge_i32_e32 vcc, v164, v159
	s_nop 1
	v_cndmask_b32_e32 v71, v225, v71, vcc
	v_cmp_ge_i32_e32 vcc, v24, v175
	s_nop 1
	v_cndmask_b32_e32 v34, v225, v34, vcc
	v_cmp_ge_i32_e32 vcc, v25, v157
	s_nop 1
	v_cndmask_b32_e32 v35, v225, v35, vcc
	v_cmp_ge_i32_e32 vcc, v26, v165
	s_nop 1
	v_cndmask_b32_e32 v32, v225, v32, vcc
	v_cmp_ge_i32_e32 vcc, v27, v156
	s_nop 1
	v_cndmask_b32_e32 v33, v225, v33, vcc
	v_cmp_ge_i32_e32 vcc, v164, v158
	s_nop 1
	v_cndmask_b32_e32 v30, v225, v30, vcc
	v_cmp_ge_i32_e32 vcc, v49, v149
	s_nop 1
	v_cndmask_b32_e32 v31, v225, v31, vcc
	v_cmp_ge_i32_e32 vcc, v164, v155
	s_nop 1
	v_cndmask_b32_e32 v28, v225, v28, vcc
	v_cmp_ge_i32_e32 vcc, v164, v147
	s_nop 1
	v_cndmask_b32_e32 v29, v225, v29, vcc
.LBB0_911:
	v_max_f32_e32 v36, v74, v75
	v_max_f32_e32 v37, v70, v71
	v_max_f32_e32 v38, v34, v35
	v_max_f32_e32 v39, v32, v33
	v_max_f32_e32 v41, v28, v28
	v_max_f32_e32 v40, v41, v29
	v_max3_f32 v40, v30, v31, v40
	v_max3_f32 v36, v76, v77, v36
	v_max3_f32 v37, v72, v73, v37
	v_max3_f32 v38, v38, v39, v40
	v_max3_f32 v36, v36, v37, v38
	v_mov_b32_e32 v37, v36
	s_nop 1
	v_permlane16_swap_b32_e32 v36, v37
	v_max_f32_e32 v36, v36, v37
	v_mov_b32_e32 v37, v36
	s_add_i32 s44, s44, 1
	s_andn2_b64 vcc, exec, s[38:39]
	v_permlane32_swap_b32_e32 v36, v37
	s_cbranch_vccnz .LBB0_913
	s_bitcmp1_b32 s44, 0
	s_cselect_b32 s38, 0x4800, 0
	v_add_u32_e32 v38, s38, v202
	s_waitcnt vmcnt(0)
	ds_write_b128 v38, v[16:19]
.LBB0_913:
	v_add_u32_e32 v38, s45, v161
	v_add_u32_e32 v39, 0xfffffc0c, v38
	v_cvt_f32_i32_e32 v39, v39
	v_max_f32_e32 v36, v36, v37
	v_fmac_f32_e32 v36, v154, v39
	v_max_f32_e32 v36, v79, v36
	v_fma_f32 v37, v154, v39, -v36
	v_add_f32_e32 v39, v76, v37
	v_exp_f32_e32 v39, v39
	v_add_f32_e32 v40, v77, v37
	v_exp_f32_e32 v40, v40
	v_add_f32_e32 v41, v75, v37
	v_add_f32_e32 v39, 0, v39
	v_exp_f32_e32 v41, v41
	v_add_f32_e32 v39, v40, v39
	v_add_f32_e32 v40, v74, v37
	v_exp_f32_e32 v40, v40
	v_add_f32_e32 v42, v72, v37
	v_exp_f32_e32 v42, v42
	v_add_f32_e32 v43, v73, v37
	v_exp_f32_e32 v43, v43
	v_add_f32_e32 v39, v40, v39
	v_add_f32_e32 v40, v70, v37
	v_add_f32_e32 v39, v41, v39
	v_exp_f32_e32 v40, v40
	v_add_f32_e32 v41, v71, v37
	v_exp_f32_e32 v41, v41
	v_add_f32_e32 v34, v34, v37
	v_add_f32_e32 v39, v42, v39
	v_exp_f32_e32 v34, v34
	v_add_f32_e32 v35, v35, v37
	v_add_f32_e32 v39, v43, v39
	v_exp_f32_e32 v35, v35
	v_add_f32_e32 v32, v32, v37
	v_add_f32_e32 v39, v40, v39
	v_exp_f32_e32 v32, v32
	v_add_f32_e32 v33, v33, v37
	v_add_f32_e32 v39, v41, v39
	v_exp_f32_e32 v33, v33
	v_add_f32_e32 v30, v30, v37
	v_add_f32_e32 v34, v34, v39
	v_exp_f32_e32 v30, v30
	v_add_f32_e32 v31, v31, v37
	v_add_f32_e32 v34, v35, v34
	v_exp_f32_e32 v31, v31
	v_add_f32_e32 v32, v32, v34
	v_add_f32_e32 v32, v33, v32
	v_add_f32_e32 v30, v30, v32
	v_add_f32_e32 v28, v28, v37
	v_add_f32_e32 v30, v31, v30
	v_exp_f32_e32 v31, v28
	v_add_f32_e32 v28, v29, v37
	v_exp_f32_e32 v29, v28
	v_sub_f32_e32 v28, v79, v36
	v_exp_f32_e32 v32, v28
	v_add_u32_e32 v28, 0xfffffc10, v38
	v_cvt_f32_i32_e32 v33, v28
	v_max_f32_e32 v28, v53, v89
	v_fmac_f32_e32 v28, v154, v33
	v_max_f32_e32 v28, v50, v28
	v_fma_f32 v33, v154, v33, -v28
	v_add_f32_e32 v34, v68, v33
	v_exp_f32_e32 v34, v34
	v_add_f32_e32 v30, v31, v30
	v_add_f32_e32 v29, v29, v30
	v_add_f32_e32 v31, v69, v33
	v_fmac_f32_e32 v29, v78, v32
	v_exp_f32_e32 v31, v31
	v_add_f32_e32 v32, v66, v33
	v_exp_f32_e32 v32, v32
	v_add_f32_e32 v30, 0, v34
	v_add_f32_e32 v34, v67, v33
	v_exp_f32_e32 v34, v34
	v_add_f32_e32 v35, v64, v33
	v_exp_f32_e32 v35, v35
	v_add_f32_e32 v30, v31, v30
	v_add_f32_e32 v31, v65, v33
	v_add_f32_e32 v30, v32, v30
	v_exp_f32_e32 v31, v31
	v_add_f32_e32 v32, v62, v33
	v_exp_f32_e32 v32, v32
	v_add_f32_e32 v30, v34, v30
	v_add_f32_e32 v34, v63, v33
	v_add_f32_e32 v30, v35, v30
	v_exp_f32_e32 v34, v34
	v_add_f32_e32 v35, v60, v33
	v_exp_f32_e32 v35, v35
	v_add_f32_e32 v30, v31, v30
	v_add_f32_e32 v31, v61, v33
	v_add_f32_e32 v30, v32, v30
	v_exp_f32_e32 v31, v31
	v_add_f32_e32 v32, v58, v33
	v_exp_f32_e32 v32, v32
	v_add_f32_e32 v30, v34, v30
	v_add_f32_e32 v34, v59, v33
	v_add_f32_e32 v30, v35, v30
	v_exp_f32_e32 v34, v34
	v_add_f32_e32 v35, v56, v33
	v_exp_f32_e32 v35, v35
	v_add_f32_e32 v30, v31, v30
	v_add_f32_e32 v31, v57, v33
	v_add_f32_e32 v30, v32, v30
	v_exp_f32_e32 v31, v31
	v_add_f32_e32 v32, v54, v33
	v_exp_f32_e32 v32, v32
	v_add_f32_e32 v33, v55, v33
	v_add_f32_e32 v30, v34, v30
	v_exp_f32_e32 v33, v33
	v_sub_f32_e32 v34, v50, v28
	v_add_f32_e32 v30, v35, v30
	v_exp_f32_e32 v34, v34
	v_add_f32_e32 v30, v31, v30
	v_add_f32_e32 v30, v32, v30
	s_waitcnt lgkmcnt(0)
	s_barrier
	v_add_f32_e32 v30, v33, v30
	s_addk_i32 s45, 0x400
	v_fmac_f32_e32 v30, v48, v34
	s_cmp_lg_u32 s20, s44
	v_add_u32_e32 v52, 64, v52
	s_cbranch_scc0 .LBB0_916
	v_mov_b32_e32 v78, v29
	v_mov_b32_e32 v79, v36
	v_mov_b32_e32 v48, v30
	v_mov_b32_e32 v50, v28
	s_cmp_lt_i32 s44, s46
	s_cselect_b64 s[38:39], -1, 0
	s_cmp_ge_i32 s44, s46
	s_cbranch_scc0 .LBB0_906
	s_branch .LBB0_907

; template <int MODE>
; __device__ __forceinline__ void nsa_soft(f32x4 (&st)[4], const float (&Bl)[16], float cl, bool fast, int keybase, int t, bool sel, float& m2, float& l, f32x4 (&o)[4], float lfin, LAS float* imp, int lane) {
;     ...
;     } else {
;         float mloc = fmaxf(fmaxf(fmaxf(st[0][0], st[0][1]), fmaxf(st[0][2], st[0][3])), fmaxf(fmaxf(st[1][0], st[1][1]), fmaxf(st[1][2], st[1][3])));
;         mloc = fmaxf(mloc, fmaxf(fmaxf(fmaxf(st[2][0], st[2][1]), fmaxf(st[2][2], st[2][3])), fmaxf(fmaxf(st[3][0], st[3][1]), fmaxf(st[3][2], st[3][3]))));
;         mloc = xrow16_max(mloc);
;         const float mnew = fmaxf(m2, mloc + cl); const float alpha = __builtin_amdgcn_exp2f(m2 - mnew); m2 = mnew;
;         const float sh = cl - mnew;
;         float ps = 0.f;
; #pragma unroll
;         for (int tau = 0; tau < 4; ++tau)
; #pragma unroll
;             for (int r = 0; r < 4; ++r) { const float p = __builtin_amdgcn_exp2f(st[tau][r] + sh); st[tau][r] = p; ps += p; }
;         l = l * alpha + ps;
.LBB0_1042:
	v_lshrrev_b64 v[68:69], s62, v[68:69]
	v_and_b32_e32 v68, 1, v68
	v_cmp_eq_u32_e64 s[12:13], 1, v68
	v_max_f32_e32 v68, v86, v87
	v_max_f32_e32 v69, v82, v83
	v_max_f32_e32 v190, v80, v81
	v_max_f32_e32 v191, v78, v79
	v_max_f32_e32 v192, v74, v75
	v_max3_f32 v192, v76, v77, v192
	v_max3_f32 v68, v188, v189, v68
	v_max3_f32 v69, v84, v85, v69
	v_max3_f32 v190, v190, v191, v192
	v_max3_f32 v68, v68, v69, v190
	v_mov_b32_e32 v69, v68
	s_nop 1
	v_permlane16_swap_b32_e32 v68, v69
	v_max_f32_e32 v242, v68, v69
	v_mov_b32_e32 v241, v242
	s_nop 1
	v_permlane32_swap_b32_e32 v242, v241
	v_pk_fma_f32 v[194:195], v[56:57], s[22:23], v[170:171] op_sel_hi:[1,0,1]
	v_pk_fma_f32 v[192:193], v[58:59], s[22:23], v[172:173] op_sel_hi:[1,0,1]
	v_pk_fma_f32 v[190:191], v[60:61], s[22:23], v[174:175] op_sel_hi:[1,0,1]
	v_pk_fma_f32 v[68:69], v[62:63], s[22:23], v[176:177] op_sel_hi:[1,0,1]
	v_pk_fma_f32 v[62:63], v[64:65], s[22:23], v[178:179] op_sel_hi:[1,0,1]
	v_pk_fma_f32 v[60:61], v[66:67], s[22:23], v[180:181] op_sel_hi:[1,0,1]
	v_pk_fma_f32 v[56:57], v[70:71], s[22:23], v[182:183] op_sel_hi:[1,0,1]
	s_andn2_b64 vcc, exec, s[58:59]
	v_pk_fma_f32 v[58:59], v[72:73], s[22:23], v[184:185] op_sel_hi:[1,0,1]
	s_cbranch_vccnz .LBB0_1044
	v_cmp_ge_i32_e32 vcc, v164, v236
	s_and_b64 vcc, s[12:13], vcc
	s_nop 0
	v_cndmask_b32_e32 v194, v225, v194, vcc
	v_cmp_gt_i32_e32 vcc, v164, v236
	s_and_b64 vcc, s[12:13], vcc
	s_nop 0
	v_cndmask_b32_e32 v195, v225, v195, vcc
	v_cmp_ge_i32_e32 vcc, v164, v240
	s_and_b64 vcc, s[12:13], vcc
	s_nop 0
	v_cndmask_b32_e32 v192, v225, v192, vcc
	v_cmp_ge_i32_e32 vcc, v164, v239
	s_and_b64 vcc, s[12:13], vcc
	s_nop 0
	v_cndmask_b32_e32 v193, v225, v193, vcc
	v_cmp_ge_i32_e32 vcc, v162, v236
	s_and_b64 vcc, s[12:13], vcc
	s_nop 0
	v_cndmask_b32_e32 v190, v225, v190, vcc
	v_cmp_ge_i32_e32 vcc, v164, v238
	s_and_b64 vcc, s[12:13], vcc
	s_nop 0
	v_cndmask_b32_e32 v191, v225, v191, vcc
	v_cmp_ge_i32_e32 vcc, v164, v237
	s_and_b64 vcc, s[12:13], vcc
	s_nop 0
	v_cndmask_b32_e32 v68, v225, v68, vcc
	v_cmp_ge_i32_e32 vcc, v164, v235
	s_and_b64 vcc, s[12:13], vcc
	s_nop 0
	v_cndmask_b32_e32 v69, v225, v69, vcc
	v_cmp_ge_i32_e32 vcc, v164, v234
	s_and_b64 vcc, s[12:13], vcc
	s_nop 0
	v_cndmask_b32_e32 v62, v225, v62, vcc
	v_cmp_ge_i32_e32 vcc, v164, v233
	s_and_b64 vcc, s[12:13], vcc
	s_nop 0
	v_cndmask_b32_e32 v63, v225, v63, vcc
	v_cmp_ge_i32_e32 vcc, v164, v232
	s_and_b64 vcc, s[12:13], vcc
	s_nop 0
	v_cndmask_b32_e32 v60, v225, v60, vcc
	v_cmp_ge_i32_e32 vcc, v164, v231
	s_and_b64 vcc, s[12:13], vcc
	s_nop 0
	v_cndmask_b32_e32 v61, v225, v61, vcc
	v_cmp_ge_i32_e32 vcc, v164, v230
	s_and_b64 vcc, s[12:13], vcc
	s_nop 0
	v_cndmask_b32_e32 v56, v225, v56, vcc
	v_cmp_ge_i32_e32 vcc, v164, v229
	s_and_b64 vcc, s[12:13], vcc
	s_nop 0
	v_cndmask_b32_e32 v57, v225, v57, vcc
	v_cmp_ge_i32_e32 vcc, v164, v228
	s_and_b64 vcc, s[12:13], vcc
	s_nop 0
	v_cndmask_b32_e32 v58, v225, v58, vcc
	v_cmp_ge_i32_e32 vcc, v164, v227
	s_and_b64 vcc, s[12:13], vcc
	s_nop 0
	v_cndmask_b32_e32 v59, v225, v59, vcc
.LBB0_1044:
	v_sub_u32_e32 v64, s20, v162
	v_cvt_f32_i32_e32 v64, v64
	s_xor_b64 s[10:11], s[10:11], -1
	s_and_b64 vcc, s[56:57], s[10:11]
	v_mul_f32_e32 v64, v154, v64
	v_cndmask_b32_e32 v64, v64, v225, vcc
	v_max_f32_e32 v65, v242, v241
	v_add_f32_e32 v65, v64, v65
	v_max_f32_e32 v227, v163, v65
	v_sub_f32_e32 v64, v64, v227
	v_add_f32_e32 v65, v188, v64
	v_exp_f32_e32 v65, v65
	v_add_f32_e32 v66, v189, v64
	v_exp_f32_e32 v66, v66
	v_add_f32_e32 v67, v86, v64
	v_exp_f32_e32 v67, v67
	v_add_f32_e32 v71, v87, v64
	v_exp_f32_e32 v71, v71
	v_add_f32_e32 v73, v84, v64
	v_add_f32_e32 v70, 0, v65
	v_exp_f32_e32 v73, v73
	v_add_f32_e32 v84, v85, v64
	v_add_f32_e32 v70, v66, v70
	v_exp_f32_e32 v84, v84
	v_add_f32_e32 v82, v82, v64
	v_add_f32_e32 v70, v67, v70
	v_exp_f32_e32 v82, v82
	v_add_f32_e32 v70, v71, v70
	v_add_f32_e32 v70, v73, v70
	v_add_f32_e32 v70, v84, v70
	v_sub_f32_e32 v72, v163, v227
	v_add_f32_e32 v163, v82, v70
	v_add_f32_e32 v70, v83, v64
	v_exp_f32_e32 v83, v70
	v_add_f32_e32 v70, v80, v64
	v_exp_f32_e32 v80, v70
	v_add_f32_e32 v70, v81, v64
	v_exp_f32_e32 v81, v70
	v_add_f32_e32 v70, v78, v64
	v_exp_f32_e32 v78, v70
	v_add_f32_e32 v70, v79, v64
	v_exp_f32_e32 v79, v70
	v_add_f32_e32 v70, v76, v64
	v_exp_f32_e32 v76, v70
	v_add_f32_e32 v70, v77, v64
	v_exp_f32_e32 v77, v70
	v_add_f32_e32 v70, v74, v64
	v_exp_f32_e32 v188, v70
	v_sub_u32_e32 v70, s20, v164
	v_cvt_f32_i32_e32 v70, v70
	v_add_f32_e32 v64, v75, v64
	v_exp_f32_e32 v189, v64
	v_mul_f32_e32 v64, v154, v70
	v_max_f32_e32 v70, v192, v193
	v_max_f32_e32 v74, v68, v69
	v_max_f32_e32 v75, v62, v63
	v_max_f32_e32 v85, v60, v61
	v_max_f32_e32 v86, v58, v59
	v_max3_f32 v86, v56, v57, v86
	v_max3_f32 v70, v194, v195, v70
	v_max3_f32 v74, v190, v191, v74
	v_max3_f32 v75, v75, v85, v86
	v_max3_f32 v70, v70, v74, v75
	v_mov_b32_e32 v74, v70
	s_nop 1
	v_permlane16_swap_b32_e32 v70, v74
	v_max_f32_e32 v70, v70, v74
	v_mov_b32_e32 v74, v70
	s_xor_b64 s[10:11], s[12:13], -1
	s_nop 0
	v_permlane32_swap_b32_e32 v70, v74
	s_and_b64 vcc, s[56:57], s[10:11]
	v_cndmask_b32_e32 v64, v64, v225, vcc
	v_max_f32_e32 v70, v70, v74
	v_add_f32_e32 v70, v64, v70
	v_max_f32_e32 v232, v161, v70
	v_sub_f32_e32 v64, v64, v232
	v_add_f32_e32 v70, v194, v64
	v_exp_f32_e32 v233, v70
	v_add_f32_e32 v70, v195, v64
	v_exp_f32_e32 v195, v70
	v_add_f32_e32 v70, v192, v64
; #define LAS __attribute__((address_space(3)))
; __device__ __forceinline__ f32x4 mfma16(bf16x8 a, bf16x8 b, f32x4 c) { return __builtin_amdgcn_mfma_f32_16x16x32_bf16(a, b, c, 0, 0, 0); }
; template <int MODE>
; __device__ __forceinline__ void nsa_soft(f32x4 (&st)[4], const float (&Bl)[16], float cl, bool fast, int keybase, int t, bool sel, float& m2, float& l, f32x4 (&o)[4], float lfin, LAS float* imp, int lane) {
;     ...
;         for (int tau = 0; tau < 4; ++tau)
; #pragma unroll
;             for (int r = 0; r < 4; ++r) { const float p = __builtin_amdgcn_exp2f(st[tau][r] + sh); st[tau][r] = p; ps += p; }
;         l = l * alpha + ps;
;         if (MODE != 0) {
; #pragma unroll
;             for (int dt = 0; dt < 4; ++dt) o[dt] = o[dt] * alpha;
; template <int MODE> ...
;     ...
;     if (MODE != 0) {
;         bf16x8 pb[2][2];
; #pragma unroll
;         for (int s = 0; s < 2; ++s) { pb[s][0] = pack_p(st[s][0], st[s][1]); pb[s][1] = pack_p(st[s][2], st[s][3]); }
; #pragma unroll
;         for (int dt = 0; dt < 4; ++dt) { const LAS bf16* vp = vt + (dt * 16 + (lane & 15)) * KT_LD + 8 * kg;
;             const bf16x8 v0 = *(const LAS bf16x8*)(vp), v1 = *(const LAS bf16x8*)(vp + 32);
; #pragma unroll
;             for (int s = 0; s < 2; ++s) { o[s][dt] = mfma16(v0, pb[s][0], o[s][dt]); o[s][dt] = mfma16(v1, pb[s][1], o[s][dt]); } }
;     }
	v_add_f32_e32 v56, v56, v64
	v_exp_f32_e32 v234, v70
	v_add_f32_e32 v70, v193, v64
	v_exp_f32_e32 v244, v56
	v_add_f32_e32 v56, v57, v64
	v_exp_f32_e32 v235, v70
	v_add_f32_e32 v70, v190, v64
	v_add_f32_e32 v68, v68, v64
	v_add_f32_e32 v62, v62, v64
	v_add_f32_e32 v60, v60, v64
	v_exp_f32_e32 v245, v56
	v_add_f32_e32 v56, v58, v64
	v_exp_f32_e32 v236, v70
	v_add_f32_e32 v70, v191, v64
	v_exp_f32_e32 v238, v68
	v_add_f32_e32 v68, v69, v64
	v_exp_f32_e32 v240, v62
	v_add_f32_e32 v62, v63, v64
	v_exp_f32_e32 v242, v60
	v_add_f32_e32 v60, v61, v64
	v_exp_f32_e32 v246, v56
	v_add_f32_e32 v56, v59, v64
	v_exp_f32_e32 v237, v70
	v_exp_f32_e32 v239, v68
	v_exp_f32_e32 v241, v62
	v_exp_f32_e32 v243, v60
	v_exp_f32_e32 v247, v56
	v_cvt_pk_bf16_f32 v68, v65, v66
	v_cvt_pk_bf16_f32 v69, v67, v71
	v_cvt_pk_bf16_f32 v70, v73, v84
	v_cvt_pk_bf16_f32 v71, v82, v83
	v_cvt_pk_bf16_f32 v84, v80, v81
	v_cvt_pk_bf16_f32 v85, v78, v79
	v_cvt_pk_bf16_f32 v86, v76, v77
	v_cvt_pk_bf16_f32 v87, v188, v189
	v_cvt_pk_bf16_f32 v190, v233, v195
	v_cvt_pk_bf16_f32 v191, v234, v235
	v_cvt_pk_bf16_f32 v192, v236, v237
	v_cvt_pk_bf16_f32 v193, v238, v239
	v_cvt_pk_bf16_f32 v228, v240, v241
	v_cvt_pk_bf16_f32 v229, v242, v243
	v_cvt_pk_bf16_f32 v230, v244, v245
	v_cvt_pk_bf16_f32 v231, v246, v247
	ds_read_b128 v[56:59], v165 offset:9216
	v_add_f32_e32 v60, v83, v163
	v_exp_f32_e32 v64, v72
	v_add_f32_e32 v65, v80, v60
	ds_read_b128 v[60:63], v165 offset:9280
	v_add_f32_e32 v65, v81, v65
	v_pk_mul_f32 v[54:55], v[54:55], v[64:65] op_sel_hi:[1,0]
	v_pk_mul_f32 v[52:53], v[52:53], v[64:65] op_sel_hi:[1,0]
	v_sub_f32_e32 v66, v161, v232
	v_exp_f32_e32 v194, v66
	s_waitcnt lgkmcnt(1)
	v_mfma_f32_16x16x32_bf16 v[52:55], v[56:59], v[68:71], v[52:55]
	v_add_f32_e32 v65, v78, v65
	v_add_f32_e32 v65, v79, v65
	v_pk_mul_f32 v[50:51], v[50:51], v[194:195] op_sel_hi:[1,0]
	s_waitcnt lgkmcnt(0)
	v_mfma_f32_16x16x32_bf16 v[72:75], v[60:63], v[84:87], v[52:55]
	v_mul_f32_e64 v48, v48, v194
	v_mul_f32_e64 v49, v49, v194
	v_pk_mul_f32 v[42:43], v[42:43], v[194:195] op_sel_hi:[1,0]
	v_pk_mul_f32 v[40:41], v[40:41], v[194:195] op_sel_hi:[1,0]
	ds_read_b128 v[52:55], v165 offset:11520
	v_mfma_f32_16x16x32_bf16 v[48:51], v[56:59], v[190:193], v[48:51]
	v_add_f32_e32 v56, v76, v65
	v_add_f32_e32 v65, v77, v56
	ds_read_b128 v[56:59], v165 offset:11584
	v_pk_mul_f32 v[46:47], v[46:47], v[64:65] op_sel_hi:[1,0]
	v_pk_mul_f32 v[44:45], v[44:45], v[64:65] op_sel_hi:[1,0]
	v_mfma_f32_16x16x32_bf16 v[60:63], v[60:63], v[228:231], v[48:51]
	v_mul_f32_e64 v38, v38, v64
	v_mul_f32_e64 v39, v39, v64
	v_pk_mul_f32 v[36:37], v[36:37], v[64:65] op_sel_hi:[1,0]
	v_pk_mul_f32 v[30:31], v[30:31], v[194:195] op_sel_hi:[1,0]
	s_waitcnt lgkmcnt(1)
	v_mfma_f32_16x16x32_bf16 v[44:47], v[52:55], v[68:71], v[44:47]
	v_add_f32_e32 v48, v188, v65
	v_add_f32_e32 v189, v189, v48
	ds_read_b128 v[48:51], v165 offset:13888
	s_waitcnt lgkmcnt(1)
	v_mfma_f32_16x16x32_bf16 v[76:79], v[56:59], v[84:87], v[44:47]
	v_mul_f32_e64 v28, v28, v194
	v_mul_f32_e64 v29, v29, v194
	v_fmac_f32_e32 v189, v187, v64
	v_pk_mul_f32 v[34:35], v[34:35], v[64:65] op_sel_hi:[1,0]
	ds_read_b128 v[44:47], v165 offset:13824
	v_mfma_f32_16x16x32_bf16 v[40:43], v[52:55], v[190:193], v[40:43]
	v_mul_f32_e64 v32, v32, v64
	v_mul_f32_e64 v33, v33, v64
	v_pk_mul_f32 v[26:27], v[26:27], v[194:195] op_sel_hi:[1,0]
	v_pk_mul_f32 v[24:25], v[24:25], v[194:195] op_sel_hi:[1,0]
	s_waitcnt lgkmcnt(0)
	v_mfma_f32_16x16x32_bf16 v[36:39], v[44:47], v[68:71], v[36:39]
	v_mov_b64_e32 v[52:53], v[72:73]
	v_mov_b32_e32 v187, v189
	v_mov_b32_e32 v163, v227
	v_mfma_f32_16x16x32_bf16 v[56:59], v[56:59], v[228:231], v[40:43]
	v_mov_b32_e32 v161, v232
	v_mov_b64_e32 v[54:55], v[74:75]
	s_nop 0
	v_add_f32_e32 v40, 0, v233
	v_add_f32_e32 v40, v195, v40
	v_add_f32_e32 v40, v234, v40
	v_mfma_f32_16x16x32_bf16 v[80:83], v[48:51], v[84:87], v[36:39]
	v_add_f32_e32 v40, v235, v40
	v_add_f32_e32 v40, v236, v40
	v_add_f32_e32 v40, v237, v40
	ds_read_b128 v[36:39], v226 offset:9216
	v_mfma_f32_16x16x32_bf16 v[28:31], v[44:47], v[190:193], v[28:31]
	v_add_f32_e32 v44, v238, v40
	ds_read_b128 v[40:43], v226 offset:9280
	v_mfma_f32_16x16x32_bf16 v[64:67], v[48:51], v[228:231], v[28:31]
	v_mov_b64_e32 v[48:49], v[60:61]
	v_mov_b64_e32 v[50:51], v[62:63]
	s_nop 2
	v_add_f32_e32 v28, v239, v44
	v_add_f32_e32 v28, v240, v28
	v_add_f32_e32 v44, v241, v28
	s_waitcnt lgkmcnt(1)
	v_mfma_f32_16x16x32_bf16 v[28:31], v[36:39], v[68:71], v[32:35]
	v_mfma_f32_16x16x32_bf16 v[24:27], v[36:39], v[190:193], v[24:27]
	s_nop 1
	v_add_f32_e32 v32, v242, v44
	v_add_f32_e32 v32, v243, v32
	v_add_f32_e32 v32, v244, v32
	s_waitcnt lgkmcnt(0)
	v_mfma_f32_16x16x32_bf16 v[84:87], v[40:43], v[84:87], v[28:31]
	v_mov_b64_e32 v[44:45], v[76:77]
	v_mov_b64_e32 v[36:37], v[80:81]
	v_mov_b64_e32 v[46:47], v[78:79]
	v_mfma_f32_16x16x32_bf16 v[68:71], v[40:43], v[228:231], v[24:27]
	v_add_f32_e32 v28, v245, v32
	v_add_f32_e32 v28, v246, v28
	v_add_f32_e32 v188, v247, v28
	v_fmac_f32_e32 v188, v186, v194
	v_mov_b64_e32 v[32:33], v[84:85]
	v_mov_b64_e32 v[40:41], v[56:57]
	v_mov_b64_e32 v[28:29], v[64:65]
	s_nop 0
	v_mov_b64_e32 v[24:25], v[68:69]
	v_mov_b32_e32 v186, v188
	v_mov_b64_e32 v[38:39], v[82:83]
	v_mov_b64_e32 v[34:35], v[86:87]
	v_mov_b64_e32 v[42:43], v[58:59]
	v_mov_b64_e32 v[30:31], v[66:67]
	v_mov_b64_e32 v[26:27], v[70:71]
	s_andn2_b64 vcc, exec, s[54:55]
	s_cbranch_vccnz .LBB0_1046

; template <int CTRL> __device__ __forceinline__ float dppf(float x) { return __builtin_bit_cast(float, __builtin_amdgcn_mov_dpp(__builtin_bit_cast(int, x), CTRL, 0xf, 0xf, true)); }
; template <int MODE>
; __device__ __forceinline__ void nsa_soft(f32x4 (&st)[4], const float (&Bl)[16], float cl, bool fast, int keybase, int t, bool sel, float& m2, float& l, f32x4 (&o)[4], float lfin, LAS float* imp, int lane) {
;     ...
;         for (int r = 0; r < 4; ++r) st[tau][r] = __builtin_fmaf(st[tau][r], LOG2E, Bl[tau * 4 + r]);
;     if (!fast) {
; #pragma unroll
;         for (int tau = 0; tau < 4; ++tau)
; #pragma unroll
;             for (int r = 0; r < 4; ++r) { const int off = keybase + 32 * (tau >> 1) + 8 * kg + 4 * (tau & 1) + r;
;                 int dist; bool valid;
;                 if (MODE <= 1) { dist = t - (16 * off + 31); valid = dist >= 0; }
;                 else if (MODE == 2) { dist = t - off; valid = sel && dist >= 0; }
;                 else { dist = t - off; valid = dist >= 0 && dist < 512; }
;                 st[tau][r] = valid ? st[tau][r] : -INFINITY; }
;     }
;     if (MODE == 1) {
;         const float sh = cl - lfin;
; #pragma unroll
;         for (int tau = 0; tau < 4; ++tau) {
; #pragma unroll
;             for (int r = 0; r < 4; ++r) st[tau][r] = __builtin_amdgcn_exp2f(st[tau][r] + sh);
;             float ps = (st[tau][0] + st[tau][1]) + (st[tau][2] + st[tau][3]), p3 = st[tau][3];
;             ps += dppf<DPP_XOR1>(ps); ps += dppf<DPP_XOR2>(ps); p3 += dppf<DPP_XOR1>(p3); p3 += dppf<DPP_XOR2>(p3);
;             const int j0 = (keybase >> 2) + 8 * (tau >> 1) + 2 * kg + (tau & 1);
;             if ((lane & 3) == 0) { const int tk = (lane & 15) >> 2; imp[tk * 256 + j0] += ps; if (j0 + 1 < 256) imp[tk * 256 + j0 + 1] += p3; }
;         }
;     } else {
;         float mloc = fmaxf(fmaxf(fmaxf(st[0][0], st[0][1]), fmaxf(st[0][2], st[0][3])), fmaxf(fmaxf(st[1][0], st[1][1]), fmaxf(st[1][2], st[1][3])));
;         mloc = fmaxf(mloc, fmaxf(fmaxf(fmaxf(st[2][0], st[2][1]), fmaxf(st[2][2], st[2][3])), fmaxf(fmaxf(st[3][0], st[3][1]), fmaxf(st[3][2], st[3][3]))));
;         mloc = xrow16_max(mloc);
.LBB0_1059:
	v_max_f32_e32 v182, v166, v167
	v_max_f32_e32 v183, v170, v171
	v_max_f32_e32 v184, v174, v175
	v_max_f32_e32 v185, v176, v177
	v_max_f32_e32 v232, v178, v179
	v_max3_f32 v232, v180, v181, v232
	v_max3_f32 v182, v168, v169, v182
	v_max3_f32 v183, v172, v173, v183
	v_max3_f32 v184, v184, v185, v232
	v_max3_f32 v182, v182, v183, v184
	v_mov_b32_e32 v183, v182
	s_nop 1
	v_permlane16_swap_b32_e32 v182, v183
	v_max_f32_e32 v232, v182, v183
	v_mov_b32_e32 v233, v232
	s_xor_b64 s[12:13], s[12:13], -1
	s_nop 0
	v_permlane32_swap_b32_e32 v232, v233
	v_pk_fma_f32 v[182:183], v[56:57], s[22:23], v[72:73] op_sel_hi:[1,0,1]
	v_pk_fma_f32 v[56:57], v[58:59], s[22:23], v[74:75] op_sel_hi:[1,0,1]
	v_pk_fma_f32 v[184:185], v[60:61], s[22:23], v[76:77] op_sel_hi:[1,0,1]
	v_pk_fma_f32 v[58:59], v[62:63], s[22:23], v[78:79] op_sel_hi:[1,0,1]
	v_pk_fma_f32 v[62:63], v[68:69], s[22:23], v[80:81] op_sel_hi:[1,0,1]
	v_pk_fma_f32 v[60:61], v[70:71], s[22:23], v[82:83] op_sel_hi:[1,0,1]
	v_pk_fma_f32 v[64:65], v[64:65], s[22:23], v[84:85] op_sel_hi:[1,0,1]
	s_andn2_b64 vcc, exec, s[12:13]
	v_pk_fma_f32 v[66:67], v[66:67], s[22:23], v[86:87] op_sel_hi:[1,0,1]
	s_cbranch_vccnz .LBB0_1061
	v_add_u32_e32 v68, -3, v228
	v_add_u32_e32 v69, s20, v147
	v_cmp_gt_u32_e32 vcc, s78, v68
	v_add_u32_e32 v70, -5, v228
	v_add_u32_e32 v71, -6, v228
	v_cndmask_b32_e32 v182, v225, v182, vcc
	v_cmp_lt_u32_e32 vcc, s96, v69
	v_add_u32_e32 v68, -8, v228
	v_subrev_u32_e32 v69, 36, v228
	v_cndmask_b32_e32 v183, v225, v183, vcc
	v_cmp_gt_u32_e32 vcc, s78, v70
	v_subrev_u32_e32 v70, 37, v228
	s_nop 0
	v_cndmask_b32_e32 v56, v225, v56, vcc
	v_cmp_gt_u32_e32 vcc, s78, v71
	v_subrev_u32_e32 v71, 38, v228
	s_nop 0
	v_cndmask_b32_e32 v57, v225, v57, vcc
	v_cmp_gt_u32_e32 vcc, s78, v231
	s_nop 1
	v_cndmask_b32_e32 v184, v225, v184, vcc
	v_cmp_gt_u32_e32 vcc, s78, v68
	v_subrev_u32_e32 v68, 35, v228
	s_nop 0
	v_cndmask_b32_e32 v185, v225, v185, vcc
	v_cmp_gt_u32_e32 vcc, s78, v230
	s_nop 1
	v_cndmask_b32_e32 v58, v225, v58, vcc
	v_cmp_gt_u32_e32 vcc, s78, v229
	s_nop 1
	v_cndmask_b32_e32 v59, v225, v59, vcc
	v_cmp_gt_u32_e32 vcc, s78, v68
	s_nop 1
	v_cndmask_b32_e32 v62, v225, v62, vcc
	v_cmp_gt_u32_e32 vcc, s78, v69
	s_nop 1
	v_cndmask_b32_e32 v63, v225, v63, vcc
	v_cmp_gt_u32_e32 vcc, s78, v70
	s_nop 1
	v_cndmask_b32_e32 v60, v225, v60, vcc
	v_cmp_gt_u32_e32 vcc, s78, v71
	s_nop 1
	v_cndmask_b32_e32 v61, v225, v61, vcc
	v_cmp_gt_u32_e32 vcc, s78, v226
	s_nop 1
	v_cndmask_b32_e32 v64, v225, v64, vcc
	v_cmp_gt_u32_e32 vcc, s78, v227
	s_nop 1
	v_cndmask_b32_e32 v65, v225, v65, vcc
	v_cmp_gt_u32_e32 vcc, s78, v195
	s_nop 1
	v_cndmask_b32_e32 v66, v225, v66, vcc
	v_cmp_gt_u32_e32 vcc, s78, v194
	s_nop 1
	v_cndmask_b32_e32 v67, v225, v67, vcc
; #define LAS __attribute__((address_space(3)))
; __device__ __forceinline__ f32x4 mfma16(bf16x8 a, bf16x8 b, f32x4 c) { return __builtin_amdgcn_mfma_f32_16x16x32_bf16(a, b, c, 0, 0, 0); }
; template <int MODE>
; __device__ __forceinline__ void nsa_soft(f32x4 (&st)[4], const float (&Bl)[16], float cl, bool fast, int keybase, int t, bool sel, float& m2, float& l, f32x4 (&o)[4], float lfin, LAS float* imp, int lane) {
;     ...
;     } else {
;         float mloc = fmaxf(fmaxf(fmaxf(st[0][0], st[0][1]), fmaxf(st[0][2], st[0][3])), fmaxf(fmaxf(st[1][0], st[1][1]), fmaxf(st[1][2], st[1][3])));
;         mloc = fmaxf(mloc, fmaxf(fmaxf(fmaxf(st[2][0], st[2][1]), fmaxf(st[2][2], st[2][3])), fmaxf(fmaxf(st[3][0], st[3][1]), fmaxf(st[3][2], st[3][3]))));
;         mloc = xrow16_max(mloc);
;         const float mnew = fmaxf(m2, mloc + cl); const float alpha = __builtin_amdgcn_exp2f(m2 - mnew); m2 = mnew;
;         const float sh = cl - mnew;
;         float ps = 0.f;
; #pragma unroll
;         for (int tau = 0; tau < 4; ++tau)
; #pragma unroll
;             for (int r = 0; r < 4; ++r) { const float p = __builtin_amdgcn_exp2f(st[tau][r] + sh); st[tau][r] = p; ps += p; }
;         l = l * alpha + ps;
;         if (MODE != 0) {
; #pragma unroll
;             for (int dt = 0; dt < 4; ++dt) o[dt] = o[dt] * alpha;
;         }
; template <int MODE> ...
;     ...
;     if (MODE != 0) {
;         bf16x8 pb[2][2];
; #pragma unroll
;         for (int s = 0; s < 2; ++s) { pb[s][0] = pack_p(st[s][0], st[s][1]); pb[s][1] = pack_p(st[s][2], st[s][3]); }
; #pragma unroll
;         for (int dt = 0; dt < 4; ++dt) { const LAS bf16* vp = vt + (dt * 16 + (lane & 15)) * KT_LD + 8 * kg;
;             const bf16x8 v0 = *(const LAS bf16x8*)(vp), v1 = *(const LAS bf16x8*)(vp + 32);
; #pragma unroll
;             for (int s = 0; s < 2; ++s) { o[s][dt] = mfma16(v0, pb[s][0], o[s][dt]); o[s][dt] = mfma16(v1, pb[s][1], o[s][dt]); } }
;     }
.LBB0_1061:
	v_add_u32_e32 v68, s20, v186
	v_cvt_f32_i32_e32 v69, v68
	v_max_f32_e32 v68, v232, v233
	v_fmac_f32_e32 v68, v154, v69
	v_max_f32_e32 v68, v191, v68
	v_fma_f32 v194, v154, v69, -v68
	v_add_f32_e32 v70, v169, v194
	v_add_f32_e32 v169, v170, v194
	v_add_f32_e32 v170, v171, v194
	v_add_f32_e32 v171, v174, v194
	v_add_f32_e32 v174, v177, v194
	v_add_f32_e32 v177, v178, v194
	v_add_f32_e32 v178, v179, v194
	v_add_u32_e32 v179, s20, v161
	v_add_f32_e32 v69, v168, v194
	v_add_f32_e32 v71, v166, v194
	v_add_f32_e32 v166, v167, v194
	v_add_f32_e32 v167, v172, v194
	v_add_f32_e32 v168, v173, v194
	v_add_f32_e32 v172, v175, v194
	v_add_f32_e32 v173, v176, v194
	v_add_f32_e32 v175, v180, v194
	v_add_f32_e32 v176, v181, v194
	v_cvt_f32_i32_e32 v180, v179
	v_max_f32_e32 v179, v56, v57
	v_max_f32_e32 v181, v58, v59
	v_max_f32_e32 v194, v62, v63
	v_max_f32_e32 v195, v60, v61
	v_max_f32_e32 v227, v66, v66
	v_max_f32_e32 v226, v227, v67
	v_max3_f32 v226, v64, v65, v226
	v_max3_f32 v179, v182, v183, v179
	v_max3_f32 v181, v184, v185, v181
	v_max3_f32 v194, v194, v195, v226
	v_max3_f32 v179, v179, v181, v194
	v_mov_b32_e32 v181, v179
	s_nop 1
	v_permlane16_swap_b32_e32 v179, v181
	v_max_f32_e32 v179, v179, v181
	v_mov_b32_e32 v181, v179
	s_nop 1
	v_permlane32_swap_b32_e32 v179, v181
	v_max_f32_e32 v179, v179, v181
	v_fmac_f32_e32 v179, v154, v180
	v_max_f32_e32 v179, v190, v179
	v_fma_f32 v194, v154, v180, -v179
	v_add_f32_e32 v56, v56, v194
	v_add_f32_e32 v180, v182, v194
	v_exp_f32_e32 v182, v56
	v_add_f32_e32 v56, v57, v194
	v_exp_f32_e32 v57, v56
	v_add_f32_e32 v56, v184, v194
	v_add_f32_e32 v181, v183, v194
	v_exp_f32_e32 v183, v56
	v_add_f32_e32 v56, v185, v194
	v_exp_f32_e32 v184, v56
	v_add_f32_e32 v56, v58, v194
	v_exp_f32_e32 v185, v56
	v_add_f32_e32 v56, v59, v194
	v_exp_f32_e32 v59, v56
	v_add_f32_e32 v56, v62, v194
	v_exp_f32_e32 v62, v56
	v_add_f32_e32 v56, v63, v194
	v_exp_f32_e32 v63, v56
	v_add_f32_e32 v56, v60, v194
	v_exp_f32_e32 v60, v56
	v_add_f32_e32 v56, v61, v194
	v_exp_f32_e32 v61, v56
	v_add_f32_e32 v56, v64, v194
	v_exp_f32_e32 v64, v56
	v_add_f32_e32 v56, v65, v194
	v_exp_f32_e32 v65, v56
	v_add_f32_e32 v56, v66, v194
	v_exp_f32_e32 v66, v56
	v_add_f32_e32 v56, v67, v194
	v_exp_f32_e32 v69, v69
	v_exp_f32_e32 v70, v70
	v_exp_f32_e32 v71, v71
	v_exp_f32_e32 v166, v166
	v_exp_f32_e32 v167, v167
	v_exp_f32_e32 v168, v168
	v_exp_f32_e32 v169, v169
	v_exp_f32_e32 v170, v170
	v_exp_f32_e32 v171, v171
	v_exp_f32_e32 v172, v172
	v_exp_f32_e32 v173, v173
	v_exp_f32_e32 v174, v174
	v_exp_f32_e32 v175, v175
	v_exp_f32_e32 v176, v176
	v_exp_f32_e32 v177, v177
	v_exp_f32_e32 v178, v178
	v_exp_f32_e32 v180, v180
	v_exp_f32_e32 v181, v181
	v_exp_f32_e32 v67, v56
	v_cvt_pk_bf16_f32 v226, v69, v70
	v_cvt_pk_bf16_f32 v227, v71, v166
	v_cvt_pk_bf16_f32 v228, v167, v168
	v_cvt_pk_bf16_f32 v229, v169, v170
	v_cvt_pk_bf16_f32 v230, v171, v172
	v_cvt_pk_bf16_f32 v231, v173, v174
	v_cvt_pk_bf16_f32 v232, v175, v176
	v_cvt_pk_bf16_f32 v233, v177, v178
	v_cvt_pk_bf16_f32 v234, v180, v181
	v_cvt_pk_bf16_f32 v235, v182, v57
	v_cvt_pk_bf16_f32 v236, v183, v184
	v_cvt_pk_bf16_f32 v237, v185, v59
	v_cvt_pk_bf16_f32 v238, v62, v63
	v_cvt_pk_bf16_f32 v239, v60, v61
	v_cvt_pk_bf16_f32 v240, v64, v65
	v_cvt_pk_bf16_f32 v241, v66, v67
	ds_read_b128 v[242:245], v192 offset:9216
	ds_read_b128 v[246:249], v192 offset:9280
	v_sub_f32_e32 v56, v191, v68
	v_sub_f32_e32 v58, v190, v179
	v_exp_f32_e32 v56, v56
	v_exp_f32_e32 v58, v58
	s_add_i32 s17, s17, 1
	s_andn2_b64 vcc, exec, s[10:11]
	v_pk_mul_f32 v[46:47], v[46:47], v[56:57] op_sel_hi:[1,0]
	v_pk_mul_f32 v[44:45], v[44:45], v[56:57] op_sel_hi:[1,0]
	v_pk_mul_f32 v[30:31], v[30:31], v[58:59] op_sel_hi:[1,0]
	v_pk_mul_f32 v[28:29], v[28:29], v[58:59] op_sel_hi:[1,0]
	s_waitcnt lgkmcnt(1)
	v_mfma_f32_16x16x32_bf16 v[44:47], v[242:245], v[226:229], v[44:47]
	v_mul_f32_e64 v42, v42, v56
	v_mul_f32_e64 v43, v43, v56
	v_pk_mul_f32 v[40:41], v[40:41], v[56:57] op_sel_hi:[1,0]
	v_pk_mul_f32 v[26:27], v[26:27], v[58:59] op_sel_hi:[1,0]
	v_mfma_f32_16x16x32_bf16 v[28:31], v[242:245], v[234:237], v[28:31]
	ds_read_b128 v[242:245], v192 offset:11520
	v_pk_mul_f32 v[24:25], v[24:25], v[58:59] op_sel_hi:[1,0]
	v_pk_mul_f32 v[38:39], v[38:39], v[56:57] op_sel_hi:[1,0]
	s_waitcnt lgkmcnt(1)
	v_mfma_f32_16x16x32_bf16 v[44:47], v[246:249], v[230:233], v[44:47]
	v_mul_f32_e64 v36, v36, v56
	v_mul_f32_e64 v37, v37, v56
	v_pk_mul_f32 v[22:23], v[22:23], v[58:59] op_sel_hi:[1,0]
	v_pk_mul_f32 v[20:21], v[20:21], v[58:59] op_sel_hi:[1,0]
	v_mfma_f32_16x16x32_bf16 v[28:31], v[246:249], v[238:241], v[28:31]
	ds_read_b128 v[246:249], v192 offset:11584
	v_pk_mul_f32 v[34:35], v[34:35], v[56:57] op_sel_hi:[1,0]
	v_pk_mul_f32 v[32:33], v[32:33], v[56:57] op_sel_hi:[1,0]
	s_waitcnt lgkmcnt(1)
	v_mfma_f32_16x16x32_bf16 v[40:43], v[242:245], v[226:229], v[40:43]
	v_mul_f32_e64 v18, v18, v58
	v_mul_f32_e64 v19, v19, v58
	v_pk_mul_f32 v[16:17], v[16:17], v[58:59] op_sel_hi:[1,0]
	v_mfma_f32_16x16x32_bf16 v[24:27], v[242:245], v[234:237], v[24:27]
	ds_read_b128 v[242:245], v192 offset:13824
	s_waitcnt lgkmcnt(1)
	v_mfma_f32_16x16x32_bf16 v[40:43], v[246:249], v[230:233], v[40:43]
	v_mfma_f32_16x16x32_bf16 v[24:27], v[246:249], v[238:241], v[24:27]
	ds_read_b128 v[246:249], v192 offset:13888
	s_waitcnt lgkmcnt(1)
	v_mfma_f32_16x16x32_bf16 v[36:39], v[242:245], v[226:229], v[36:39]
	v_mfma_f32_16x16x32_bf16 v[20:23], v[242:245], v[234:237], v[20:23]
	ds_read_b128 v[242:245], v193 offset:9216
	ds_read_b128 v[190:193], v193 offset:9280
	s_waitcnt lgkmcnt(1)
	v_mfma_f32_16x16x32_bf16 v[32:35], v[242:245], v[226:229], v[32:35]
	v_mfma_f32_16x16x32_bf16 v[16:19], v[242:245], v[234:237], v[16:19]
	v_mfma_f32_16x16x32_bf16 v[36:39], v[246:249], v[230:233], v[36:39]
	v_mfma_f32_16x16x32_bf16 v[20:23], v[246:249], v[238:241], v[20:23]
	s_waitcnt lgkmcnt(0)
	v_mfma_f32_16x16x32_bf16 v[32:35], v[190:193], v[230:233], v[32:35]
	v_mfma_f32_16x16x32_bf16 v[16:19], v[190:193], v[238:241], v[16:19]
	s_cbranch_vccnz .LBB0_1063
	s_bitcmp1_b32 s17, 0
	s_cselect_b32 s10, 0x4800, 0
	s_add_i32 s10, s10, 0
	s_add_i32 s10, s10, 0x10800
	v_add3_u32 v191, s10, v201, v92
	v_add3_u32 v190, s10, v206, v92
	s_waitcnt vmcnt(1)
	ds_write_b128 v191, v[48:51]
	s_waitcnt vmcnt(0)
	ds_write_b128 v190, v[52:55] offset:9216
